# phase 0 mod-vector partials rewritten: weight rows requested 16 ahead, silu values computed per half
# speedup vs baseline: 1.0183x; 1.0006x over previous
.LBB0_1108:
	v_ashrrev_i32_e32 v64, 6, v46
	v_readlane_b32 s0, v250, 7
	v_lshlrev_b32_e32 v65, 2, v46
	s_nop 0
	v_add_u32_e32 v47, s0, v64
	s_movk_i32 s0, 0x600
	v_cmp_gt_i32_e32 vcc, s0, v47
	s_and_saveexec_b64 s[0:1], vcc
	s_cbranch_execz .LBB0_1115
	v_readlane_b32 s4, v249, 14
	v_readlane_b32 s5, v249, 15
	v_readlane_b32 s6, v254, 30
	v_readlane_b32 s7, v254, 31
	v_readlane_b32 s8, v254, 32
	v_readlane_b32 s9, v254, 33
	v_readlane_b32 s16, v254, 24
	v_readlane_b32 s17, v254, 25
	v_readlane_b32 s18, v254, 28
	v_readlane_b32 s19, v254, 29
	v_readlane_b32 s12, v250, 7
	v_readlane_b32 s13, v255, 4
	v_lshrrev_b32_e32 v194, 6, v163
	v_and_b32_e32 v192, 63, v163
	v_readfirstlane_b32 s26, v194
	v_lshlrev_b32_e32 v192, 4, v192
	v_mov_b32_e32 v184, 0x1000
	v_mov_b32_e32 v185, 0x2000
	v_mov_b32_e32 v186, 0x3000
	s_add_u32 s12, s12, s26
.Lmods_item:
	s_and_b32 s2, s12, 31
	s_lshr_b32 s26, s12, 5
	s_cmp_ge_u32 s26, 24
	s_cselect_b32 s27, 1, 0
	s_mul_i32 s3, s27, 24
	s_sub_u32 s26, s26, s3
	s_lshl_b32 s26, s26, 10
	v_add_u32_e32 v191, s26, v192
	v_mov_b32_e32 v190, v191
	s_mul_i32 s26, s27, 0x1800000
	s_mul_i32 s3, s2, 0xC0000
	s_add_u32 s26, s26, s3
	s_add_u32 s14, s6, s26
	s_addc_u32 s15, s7, 0
	s_lshl_b32 s26, s2, 7
	s_add_u32 s20, s16, s26
	s_addc_u32 s21, s17, 0
	s_add_u32 s22, s18, s26
	s_addc_u32 s23, s19, 0
	s_mul_i32 s26, s2, 10
	s_mul_i32 s3, s27, 5
	s_add_u32 s26, s26, s3
	s_mul_i32 s26, s26, 0x6000
	s_add_u32 s26, s26, 0x700000
	s_add_u32 s24, s4, s26
	s_addc_u32 s25, s5, 0
	s_mul_i32 s26, s27, 0x6000
	v_add_u32_e32 v194, s26, v191
	global_load_dwordx4 v[196:199], v194, s[8:9]
	global_load_dwordx4 v[68:71], v161, s[20:21] offset:0
	global_load_dwordx4 v[72:75], v161, s[20:21] offset:16
	global_load_dwordx4 v[76:79], v161, s[20:21] offset:32
	global_load_dwordx4 v[80:83], v161, s[20:21] offset:48
	global_load_dwordx4 v[84:87], v184, s[20:21] offset:0
	global_load_dwordx4 v[88:91], v184, s[20:21] offset:16
	global_load_dwordx4 v[92:95], v184, s[20:21] offset:32
	global_load_dwordx4 v[96:99], v184, s[20:21] offset:48
	global_load_dwordx4 v[100:103], v185, s[20:21] offset:0
	global_load_dwordx4 v[104:107], v185, s[20:21] offset:16
	global_load_dwordx4 v[108:111], v185, s[20:21] offset:32
	global_load_dwordx4 v[112:115], v185, s[20:21] offset:48
	global_load_dwordx4 v[116:119], v186, s[20:21] offset:0
	global_load_dwordx4 v[120:123], v186, s[20:21] offset:16
	global_load_dwordx4 v[124:127], v186, s[20:21] offset:32
	global_load_dwordx4 v[128:131], v186, s[20:21] offset:48
	global_load_dwordx4 v[132:135], v161, s[22:23] offset:0
	global_load_dwordx4 v[136:139], v161, s[22:23] offset:16
	global_load_dwordx4 v[140:143], v161, s[22:23] offset:32
	global_load_dwordx4 v[144:147], v161, s[22:23] offset:48
	global_load_dwordx4 v[0:3], v190, s[14:15]
	v_add_u32_e32 v190, 0x6000, v190
	global_load_dwordx4 v[4:7], v190, s[14:15]
	v_add_u32_e32 v190, 0x6000, v190
	global_load_dwordx4 v[8:11], v190, s[14:15]
	v_add_u32_e32 v190, 0x6000, v190
	global_load_dwordx4 v[12:15], v190, s[14:15]
	v_add_u32_e32 v190, 0x6000, v190
	global_load_dwordx4 v[16:19], v190, s[14:15]
	v_add_u32_e32 v190, 0x6000, v190
	global_load_dwordx4 v[20:23], v190, s[14:15]
	v_add_u32_e32 v190, 0x6000, v190
	global_load_dwordx4 v[24:27], v190, s[14:15]
	v_add_u32_e32 v190, 0x6000, v190
	global_load_dwordx4 v[28:31], v190, s[14:15]
	v_add_u32_e32 v190, 0x6000, v190
	global_load_dwordx4 v[32:35], v190, s[14:15]
	v_add_u32_e32 v190, 0x6000, v190
	global_load_dwordx4 v[36:39], v190, s[14:15]
	v_add_u32_e32 v190, 0x6000, v190
	global_load_dwordx4 v[40:43], v190, s[14:15]
	v_add_u32_e32 v190, 0x6000, v190
	global_load_dwordx4 v[48:51], v190, s[14:15]
	v_add_u32_e32 v190, 0x6000, v190
	global_load_dwordx4 v[52:55], v190, s[14:15]
	v_add_u32_e32 v190, 0x6000, v190
	global_load_dwordx4 v[56:59], v190, s[14:15]
	v_add_u32_e32 v190, 0x6000, v190
	global_load_dwordx4 v[60:63], v190, s[14:15]
	v_add_u32_e32 v190, 0x6000, v190
	global_load_dwordx4 v[148:151], v190, s[14:15]
	v_add_u32_e32 v190, 0x6000, v190
	s_cmp_eq_u32 s2, 0
	s_cbranch_scc1 .Lmods_bias
	v_mov_b32_e32 v164, 0
	v_mov_b32_e32 v165, 0
	v_mov_b32_e32 v166, 0
	v_mov_b32_e32 v167, 0
	v_mov_b32_e32 v168, 0
	v_mov_b32_e32 v169, 0
	v_mov_b32_e32 v170, 0
	v_mov_b32_e32 v171, 0
	v_mov_b32_e32 v172, 0
	v_mov_b32_e32 v173, 0
	v_mov_b32_e32 v174, 0
	v_mov_b32_e32 v175, 0
	v_mov_b32_e32 v176, 0
	v_mov_b32_e32 v177, 0
	v_mov_b32_e32 v178, 0
	v_mov_b32_e32 v179, 0
	v_mov_b32_e32 v180, 0
	v_mov_b32_e32 v181, 0
	v_mov_b32_e32 v182, 0
	v_mov_b32_e32 v183, 0
	s_branch .Lmods_acc_done
.Lmods_bias:
	s_waitcnt vmcnt(16)
	v_mov_b32_e32 v164, v196
	v_mov_b32_e32 v165, v197
	v_mov_b32_e32 v166, v198
	v_mov_b32_e32 v167, v199
	v_mov_b32_e32 v168, v196
	v_mov_b32_e32 v169, v197
	v_mov_b32_e32 v170, v198
	v_mov_b32_e32 v171, v199
	v_mov_b32_e32 v172, v196
	v_mov_b32_e32 v173, v197
	v_mov_b32_e32 v174, v198
	v_mov_b32_e32 v175, v199
	v_mov_b32_e32 v176, v196
	v_mov_b32_e32 v177, v197
	v_mov_b32_e32 v178, v198
	v_mov_b32_e32 v179, v199
	v_mov_b32_e32 v180, v196
	v_mov_b32_e32 v181, v197
	v_mov_b32_e32 v182, v198
	v_mov_b32_e32 v183, v199
.Lmods_acc_done:
	s_waitcnt vmcnt(16)
	v_mul_f32_e32 v206, 0xbfb8aa3b, v68
	v_mul_f32_e32 v207, 0xbfb8aa3b, v69
	v_mul_f32_e32 v208, 0xbfb8aa3b, v70
	v_mul_f32_e32 v209, 0xbfb8aa3b, v71
	v_exp_f32_e32 v206, v206
	v_exp_f32_e32 v207, v207
	v_exp_f32_e32 v208, v208
	v_exp_f32_e32 v209, v209
	v_add_f32_e32 v206, 1.0, v206
	v_add_f32_e32 v207, 1.0, v207
	v_add_f32_e32 v208, 1.0, v208
	v_add_f32_e32 v209, 1.0, v209
	v_rcp_f32_e32 v206, v206
	v_rcp_f32_e32 v207, v207
	v_rcp_f32_e32 v208, v208
	v_rcp_f32_e32 v209, v209
	v_mul_f32_e32 v68, v68, v206
	v_mul_f32_e32 v69, v69, v207
	v_mul_f32_e32 v70, v70, v208
	v_mul_f32_e32 v71, v71, v209
	v_mul_f32_e32 v206, 0xbfb8aa3b, v72
	v_mul_f32_e32 v207, 0xbfb8aa3b, v73
	v_mul_f32_e32 v208, 0xbfb8aa3b, v74
	v_mul_f32_e32 v209, 0xbfb8aa3b, v75
	v_exp_f32_e32 v206, v206
	v_exp_f32_e32 v207, v207
	v_exp_f32_e32 v208, v208
	v_exp_f32_e32 v209, v209
	v_add_f32_e32 v206, 1.0, v206
	v_add_f32_e32 v207, 1.0, v207
	v_add_f32_e32 v208, 1.0, v208
	v_add_f32_e32 v209, 1.0, v209
	v_rcp_f32_e32 v206, v206
	v_rcp_f32_e32 v207, v207
	v_rcp_f32_e32 v208, v208
	v_rcp_f32_e32 v209, v209
	v_mul_f32_e32 v72, v72, v206
	v_mul_f32_e32 v73, v73, v207
	v_mul_f32_e32 v74, v74, v208
	v_mul_f32_e32 v75, v75, v209
	v_mul_f32_e32 v206, 0xbfb8aa3b, v76
	v_mul_f32_e32 v207, 0xbfb8aa3b, v77
	v_mul_f32_e32 v208, 0xbfb8aa3b, v78
	v_mul_f32_e32 v209, 0xbfb8aa3b, v79
	v_exp_f32_e32 v206, v206
	v_exp_f32_e32 v207, v207
	v_exp_f32_e32 v208, v208
	v_exp_f32_e32 v209, v209
	v_add_f32_e32 v206, 1.0, v206
	v_add_f32_e32 v207, 1.0, v207
	v_add_f32_e32 v208, 1.0, v208
	v_add_f32_e32 v209, 1.0, v209
	v_rcp_f32_e32 v206, v206
	v_rcp_f32_e32 v207, v207
	v_rcp_f32_e32 v208, v208
	v_rcp_f32_e32 v209, v209
	v_mul_f32_e32 v76, v76, v206
	v_mul_f32_e32 v77, v77, v207
	v_mul_f32_e32 v78, v78, v208
	v_mul_f32_e32 v79, v79, v209
	v_mul_f32_e32 v206, 0xbfb8aa3b, v80
	v_mul_f32_e32 v207, 0xbfb8aa3b, v81
	v_mul_f32_e32 v208, 0xbfb8aa3b, v82
	v_mul_f32_e32 v209, 0xbfb8aa3b, v83
	v_exp_f32_e32 v206, v206
	v_exp_f32_e32 v207, v207
	v_exp_f32_e32 v208, v208
	v_exp_f32_e32 v209, v209
	v_add_f32_e32 v206, 1.0, v206
	v_add_f32_e32 v207, 1.0, v207
	v_add_f32_e32 v208, 1.0, v208
	v_add_f32_e32 v209, 1.0, v209
	v_rcp_f32_e32 v206, v206
	v_rcp_f32_e32 v207, v207
	v_rcp_f32_e32 v208, v208
	v_rcp_f32_e32 v209, v209
	v_mul_f32_e32 v80, v80, v206
	v_mul_f32_e32 v81, v81, v207
	v_mul_f32_e32 v82, v82, v208
	v_mul_f32_e32 v83, v83, v209
	v_mul_f32_e32 v206, 0xbfb8aa3b, v84
	v_mul_f32_e32 v207, 0xbfb8aa3b, v85
	v_mul_f32_e32 v208, 0xbfb8aa3b, v86
	v_mul_f32_e32 v209, 0xbfb8aa3b, v87
	v_exp_f32_e32 v206, v206
	v_exp_f32_e32 v207, v207
	v_exp_f32_e32 v208, v208
	v_exp_f32_e32 v209, v209
	v_add_f32_e32 v206, 1.0, v206
	v_add_f32_e32 v207, 1.0, v207
	v_add_f32_e32 v208, 1.0, v208
	v_add_f32_e32 v209, 1.0, v209
	v_rcp_f32_e32 v206, v206
	v_rcp_f32_e32 v207, v207
	v_rcp_f32_e32 v208, v208
	v_rcp_f32_e32 v209, v209
	v_mul_f32_e32 v84, v84, v206
	v_mul_f32_e32 v85, v85, v207
	v_mul_f32_e32 v86, v86, v208
	v_mul_f32_e32 v87, v87, v209
	v_mul_f32_e32 v206, 0xbfb8aa3b, v88
	v_mul_f32_e32 v207, 0xbfb8aa3b, v89
	v_mul_f32_e32 v208, 0xbfb8aa3b, v90
	v_mul_f32_e32 v209, 0xbfb8aa3b, v91
	v_exp_f32_e32 v206, v206
	v_exp_f32_e32 v207, v207
	v_exp_f32_e32 v208, v208
	v_exp_f32_e32 v209, v209
	v_add_f32_e32 v206, 1.0, v206
	v_add_f32_e32 v207, 1.0, v207
	v_add_f32_e32 v208, 1.0, v208
	v_add_f32_e32 v209, 1.0, v209
	v_rcp_f32_e32 v206, v206
	v_rcp_f32_e32 v207, v207
	v_rcp_f32_e32 v208, v208
	v_rcp_f32_e32 v209, v209
	v_mul_f32_e32 v88, v88, v206
	v_mul_f32_e32 v89, v89, v207
	v_mul_f32_e32 v90, v90, v208
	v_mul_f32_e32 v91, v91, v209
	v_mul_f32_e32 v206, 0xbfb8aa3b, v92
	v_mul_f32_e32 v207, 0xbfb8aa3b, v93
	v_mul_f32_e32 v208, 0xbfb8aa3b, v94
	v_mul_f32_e32 v209, 0xbfb8aa3b, v95
	v_exp_f32_e32 v206, v206
	v_exp_f32_e32 v207, v207
	v_exp_f32_e32 v208, v208
	v_exp_f32_e32 v209, v209
	v_add_f32_e32 v206, 1.0, v206
	v_add_f32_e32 v207, 1.0, v207
	v_add_f32_e32 v208, 1.0, v208
	v_add_f32_e32 v209, 1.0, v209
	v_rcp_f32_e32 v206, v206
	v_rcp_f32_e32 v207, v207
	v_rcp_f32_e32 v208, v208
	v_rcp_f32_e32 v209, v209
	v_mul_f32_e32 v92, v92, v206
	v_mul_f32_e32 v93, v93, v207
	v_mul_f32_e32 v94, v94, v208
	v_mul_f32_e32 v95, v95, v209
	v_mul_f32_e32 v206, 0xbfb8aa3b, v96
	v_mul_f32_e32 v207, 0xbfb8aa3b, v97
	v_mul_f32_e32 v208, 0xbfb8aa3b, v98
	v_mul_f32_e32 v209, 0xbfb8aa3b, v99
	v_exp_f32_e32 v206, v206
	v_exp_f32_e32 v207, v207
	v_exp_f32_e32 v208, v208
	v_exp_f32_e32 v209, v209
	v_add_f32_e32 v206, 1.0, v206
	v_add_f32_e32 v207, 1.0, v207
	v_add_f32_e32 v208, 1.0, v208
	v_add_f32_e32 v209, 1.0, v209
	v_rcp_f32_e32 v206, v206
	v_rcp_f32_e32 v207, v207
	v_rcp_f32_e32 v208, v208
	v_rcp_f32_e32 v209, v209
	v_mul_f32_e32 v96, v96, v206
	v_mul_f32_e32 v97, v97, v207
	v_mul_f32_e32 v98, v98, v208
	v_mul_f32_e32 v99, v99, v209
	v_mul_f32_e32 v206, 0xbfb8aa3b, v100
	v_mul_f32_e32 v207, 0xbfb8aa3b, v101
	v_mul_f32_e32 v208, 0xbfb8aa3b, v102
	v_mul_f32_e32 v209, 0xbfb8aa3b, v103
	v_exp_f32_e32 v206, v206
	v_exp_f32_e32 v207, v207
	v_exp_f32_e32 v208, v208
	v_exp_f32_e32 v209, v209
	v_add_f32_e32 v206, 1.0, v206
	v_add_f32_e32 v207, 1.0, v207
	v_add_f32_e32 v208, 1.0, v208
	v_add_f32_e32 v209, 1.0, v209
	v_rcp_f32_e32 v206, v206
	v_rcp_f32_e32 v207, v207
	v_rcp_f32_e32 v208, v208
	v_rcp_f32_e32 v209, v209
	v_mul_f32_e32 v100, v100, v206
	v_mul_f32_e32 v101, v101, v207
	v_mul_f32_e32 v102, v102, v208
	v_mul_f32_e32 v103, v103, v209
	v_mul_f32_e32 v206, 0xbfb8aa3b, v104
	v_mul_f32_e32 v207, 0xbfb8aa3b, v105
	v_mul_f32_e32 v208, 0xbfb8aa3b, v106
	v_mul_f32_e32 v209, 0xbfb8aa3b, v107
	v_exp_f32_e32 v206, v206
	v_exp_f32_e32 v207, v207
	v_exp_f32_e32 v208, v208
	v_exp_f32_e32 v209, v209
	v_add_f32_e32 v206, 1.0, v206
	v_add_f32_e32 v207, 1.0, v207
	v_add_f32_e32 v208, 1.0, v208
	v_add_f32_e32 v209, 1.0, v209
	v_rcp_f32_e32 v206, v206
	v_rcp_f32_e32 v207, v207
	v_rcp_f32_e32 v208, v208
	v_rcp_f32_e32 v209, v209
	v_mul_f32_e32 v104, v104, v206
	v_mul_f32_e32 v105, v105, v207
	v_mul_f32_e32 v106, v106, v208
	v_mul_f32_e32 v107, v107, v209
	v_mul_f32_e32 v206, 0xbfb8aa3b, v108
	v_mul_f32_e32 v207, 0xbfb8aa3b, v109
	v_mul_f32_e32 v208, 0xbfb8aa3b, v110
	v_mul_f32_e32 v209, 0xbfb8aa3b, v111
	v_exp_f32_e32 v206, v206
	v_exp_f32_e32 v207, v207
	v_exp_f32_e32 v208, v208
	v_exp_f32_e32 v209, v209
	v_add_f32_e32 v206, 1.0, v206
	v_add_f32_e32 v207, 1.0, v207
	v_add_f32_e32 v208, 1.0, v208
	v_add_f32_e32 v209, 1.0, v209
	v_rcp_f32_e32 v206, v206
	v_rcp_f32_e32 v207, v207
	v_rcp_f32_e32 v208, v208
	v_rcp_f32_e32 v209, v209
	v_mul_f32_e32 v108, v108, v206
	v_mul_f32_e32 v109, v109, v207
	v_mul_f32_e32 v110, v110, v208
	v_mul_f32_e32 v111, v111, v209
	v_mul_f32_e32 v206, 0xbfb8aa3b, v112
	v_mul_f32_e32 v207, 0xbfb8aa3b, v113
	v_mul_f32_e32 v208, 0xbfb8aa3b, v114
	v_mul_f32_e32 v209, 0xbfb8aa3b, v115
	v_exp_f32_e32 v206, v206
	v_exp_f32_e32 v207, v207
	v_exp_f32_e32 v208, v208
	v_exp_f32_e32 v209, v209
	v_add_f32_e32 v206, 1.0, v206
	v_add_f32_e32 v207, 1.0, v207
	v_add_f32_e32 v208, 1.0, v208
	v_add_f32_e32 v209, 1.0, v209
	v_rcp_f32_e32 v206, v206
	v_rcp_f32_e32 v207, v207
	v_rcp_f32_e32 v208, v208
	v_rcp_f32_e32 v209, v209
	v_mul_f32_e32 v112, v112, v206
	v_mul_f32_e32 v113, v113, v207
	v_mul_f32_e32 v114, v114, v208
	v_mul_f32_e32 v115, v115, v209
	v_mul_f32_e32 v206, 0xbfb8aa3b, v116
	v_mul_f32_e32 v207, 0xbfb8aa3b, v117
	v_mul_f32_e32 v208, 0xbfb8aa3b, v118
	v_mul_f32_e32 v209, 0xbfb8aa3b, v119
	v_exp_f32_e32 v206, v206
	v_exp_f32_e32 v207, v207
	v_exp_f32_e32 v208, v208
	v_exp_f32_e32 v209, v209
	v_add_f32_e32 v206, 1.0, v206
	v_add_f32_e32 v207, 1.0, v207
	v_add_f32_e32 v208, 1.0, v208
	v_add_f32_e32 v209, 1.0, v209
	v_rcp_f32_e32 v206, v206
	v_rcp_f32_e32 v207, v207
	v_rcp_f32_e32 v208, v208
	v_rcp_f32_e32 v209, v209
	v_mul_f32_e32 v116, v116, v206
	v_mul_f32_e32 v117, v117, v207
	v_mul_f32_e32 v118, v118, v208
	v_mul_f32_e32 v119, v119, v209
	v_mul_f32_e32 v206, 0xbfb8aa3b, v120
	v_mul_f32_e32 v207, 0xbfb8aa3b, v121
	v_mul_f32_e32 v208, 0xbfb8aa3b, v122
	v_mul_f32_e32 v209, 0xbfb8aa3b, v123
	v_exp_f32_e32 v206, v206
	v_exp_f32_e32 v207, v207
	v_exp_f32_e32 v208, v208
	v_exp_f32_e32 v209, v209
	v_add_f32_e32 v206, 1.0, v206
	v_add_f32_e32 v207, 1.0, v207
	v_add_f32_e32 v208, 1.0, v208
	v_add_f32_e32 v209, 1.0, v209
	v_rcp_f32_e32 v206, v206
	v_rcp_f32_e32 v207, v207
	v_rcp_f32_e32 v208, v208
	v_rcp_f32_e32 v209, v209
	v_mul_f32_e32 v120, v120, v206
	v_mul_f32_e32 v121, v121, v207
	v_mul_f32_e32 v122, v122, v208
	v_mul_f32_e32 v123, v123, v209
	v_mul_f32_e32 v206, 0xbfb8aa3b, v124
	v_mul_f32_e32 v207, 0xbfb8aa3b, v125
	v_mul_f32_e32 v208, 0xbfb8aa3b, v126
	v_mul_f32_e32 v209, 0xbfb8aa3b, v127
	v_exp_f32_e32 v206, v206
	v_exp_f32_e32 v207, v207
	v_exp_f32_e32 v208, v208
	v_exp_f32_e32 v209, v209
	v_add_f32_e32 v206, 1.0, v206
	v_add_f32_e32 v207, 1.0, v207
	v_add_f32_e32 v208, 1.0, v208
	v_add_f32_e32 v209, 1.0, v209
	v_rcp_f32_e32 v206, v206
	v_rcp_f32_e32 v207, v207
	v_rcp_f32_e32 v208, v208
	v_rcp_f32_e32 v209, v209
	v_mul_f32_e32 v124, v124, v206
	v_mul_f32_e32 v125, v125, v207
	v_mul_f32_e32 v126, v126, v208
	v_mul_f32_e32 v127, v127, v209
	v_mul_f32_e32 v206, 0xbfb8aa3b, v128
	v_mul_f32_e32 v207, 0xbfb8aa3b, v129
	v_mul_f32_e32 v208, 0xbfb8aa3b, v130
	v_mul_f32_e32 v209, 0xbfb8aa3b, v131
	v_exp_f32_e32 v206, v206
	v_exp_f32_e32 v207, v207
	v_exp_f32_e32 v208, v208
	v_exp_f32_e32 v209, v209
	v_add_f32_e32 v206, 1.0, v206
	v_add_f32_e32 v207, 1.0, v207
	v_add_f32_e32 v208, 1.0, v208
	v_add_f32_e32 v209, 1.0, v209
	v_rcp_f32_e32 v206, v206
	v_rcp_f32_e32 v207, v207
	v_rcp_f32_e32 v208, v208
	v_rcp_f32_e32 v209, v209
	v_mul_f32_e32 v128, v128, v206
	v_mul_f32_e32 v129, v129, v207
	v_mul_f32_e32 v130, v130, v208
	v_mul_f32_e32 v131, v131, v209
	v_mul_f32_e32 v206, 0xbfb8aa3b, v132
	v_mul_f32_e32 v207, 0xbfb8aa3b, v133
	v_mul_f32_e32 v208, 0xbfb8aa3b, v134
	v_mul_f32_e32 v209, 0xbfb8aa3b, v135
	v_exp_f32_e32 v206, v206
	v_exp_f32_e32 v207, v207
	v_exp_f32_e32 v208, v208
	v_exp_f32_e32 v209, v209
	v_add_f32_e32 v206, 1.0, v206
	v_add_f32_e32 v207, 1.0, v207
	v_add_f32_e32 v208, 1.0, v208
	v_add_f32_e32 v209, 1.0, v209
	v_rcp_f32_e32 v206, v206
	v_rcp_f32_e32 v207, v207
	v_rcp_f32_e32 v208, v208
	v_rcp_f32_e32 v209, v209
	v_mul_f32_e32 v132, v132, v206
	v_mul_f32_e32 v133, v133, v207
	v_mul_f32_e32 v134, v134, v208
	v_mul_f32_e32 v135, v135, v209
	v_mul_f32_e32 v206, 0xbfb8aa3b, v136
	v_mul_f32_e32 v207, 0xbfb8aa3b, v137
	v_mul_f32_e32 v208, 0xbfb8aa3b, v138
	v_mul_f32_e32 v209, 0xbfb8aa3b, v139
	v_exp_f32_e32 v206, v206
	v_exp_f32_e32 v207, v207
	v_exp_f32_e32 v208, v208
	v_exp_f32_e32 v209, v209
	v_add_f32_e32 v206, 1.0, v206
	v_add_f32_e32 v207, 1.0, v207
	v_add_f32_e32 v208, 1.0, v208
	v_add_f32_e32 v209, 1.0, v209
	v_rcp_f32_e32 v206, v206
	v_rcp_f32_e32 v207, v207
	v_rcp_f32_e32 v208, v208
	v_rcp_f32_e32 v209, v209
	v_mul_f32_e32 v136, v136, v206
	v_mul_f32_e32 v137, v137, v207
	v_mul_f32_e32 v138, v138, v208
	v_mul_f32_e32 v139, v139, v209
	v_mul_f32_e32 v206, 0xbfb8aa3b, v140
	v_mul_f32_e32 v207, 0xbfb8aa3b, v141
	v_mul_f32_e32 v208, 0xbfb8aa3b, v142
	v_mul_f32_e32 v209, 0xbfb8aa3b, v143
	v_exp_f32_e32 v206, v206
	v_exp_f32_e32 v207, v207
	v_exp_f32_e32 v208, v208
	v_exp_f32_e32 v209, v209
	v_add_f32_e32 v206, 1.0, v206
	v_add_f32_e32 v207, 1.0, v207
	v_add_f32_e32 v208, 1.0, v208
	v_add_f32_e32 v209, 1.0, v209
	v_rcp_f32_e32 v206, v206
	v_rcp_f32_e32 v207, v207
	v_rcp_f32_e32 v208, v208
	v_rcp_f32_e32 v209, v209
	v_mul_f32_e32 v140, v140, v206
	v_mul_f32_e32 v141, v141, v207
	v_mul_f32_e32 v142, v142, v208
	v_mul_f32_e32 v143, v143, v209
	v_mul_f32_e32 v206, 0xbfb8aa3b, v144
	v_mul_f32_e32 v207, 0xbfb8aa3b, v145
	v_mul_f32_e32 v208, 0xbfb8aa3b, v146
	v_mul_f32_e32 v209, 0xbfb8aa3b, v147
	v_exp_f32_e32 v206, v206
	v_exp_f32_e32 v207, v207
	v_exp_f32_e32 v208, v208
	v_exp_f32_e32 v209, v209
	v_add_f32_e32 v206, 1.0, v206
	v_add_f32_e32 v207, 1.0, v207
	v_add_f32_e32 v208, 1.0, v208
	v_add_f32_e32 v209, 1.0, v209
	v_rcp_f32_e32 v206, v206
	v_rcp_f32_e32 v207, v207
	v_rcp_f32_e32 v208, v208
	v_rcp_f32_e32 v209, v209
	v_mul_f32_e32 v144, v144, v206
	v_mul_f32_e32 v145, v145, v207
	v_mul_f32_e32 v146, v146, v208
	v_mul_f32_e32 v147, v147, v209
	s_waitcnt vmcnt(15)
	v_pk_fma_f32 v[164:165], v[0:1], v[68:69], v[164:165] op_sel_hi:[1,0,1]
	v_pk_fma_f32 v[166:167], v[2:3], v[68:69], v[166:167] op_sel_hi:[1,0,1]
	v_pk_fma_f32 v[168:169], v[0:1], v[84:85], v[168:169] op_sel_hi:[1,0,1]
	v_pk_fma_f32 v[170:171], v[2:3], v[84:85], v[170:171] op_sel_hi:[1,0,1]
	v_pk_fma_f32 v[172:173], v[0:1], v[100:101], v[172:173] op_sel_hi:[1,0,1]
	v_pk_fma_f32 v[174:175], v[2:3], v[100:101], v[174:175] op_sel_hi:[1,0,1]
	v_pk_fma_f32 v[176:177], v[0:1], v[116:117], v[176:177] op_sel_hi:[1,0,1]
	v_pk_fma_f32 v[178:179], v[2:3], v[116:117], v[178:179] op_sel_hi:[1,0,1]
	v_pk_fma_f32 v[180:181], v[0:1], v[132:133], v[180:181] op_sel_hi:[1,0,1]
	v_pk_fma_f32 v[182:183], v[2:3], v[132:133], v[182:183] op_sel_hi:[1,0,1]
	global_load_dwordx4 v[0:3], v190, s[14:15]
	v_add_u32_e32 v190, 0x6000, v190
	s_waitcnt vmcnt(15)
	v_pk_fma_f32 v[164:165], v[4:5], v[68:69], v[164:165] op_sel:[0,1,0]
	v_pk_fma_f32 v[166:167], v[6:7], v[68:69], v[166:167] op_sel:[0,1,0]
	v_pk_fma_f32 v[168:169], v[4:5], v[84:85], v[168:169] op_sel:[0,1,0]
	v_pk_fma_f32 v[170:171], v[6:7], v[84:85], v[170:171] op_sel:[0,1,0]
	v_pk_fma_f32 v[172:173], v[4:5], v[100:101], v[172:173] op_sel:[0,1,0]
	v_pk_fma_f32 v[174:175], v[6:7], v[100:101], v[174:175] op_sel:[0,1,0]
	v_pk_fma_f32 v[176:177], v[4:5], v[116:117], v[176:177] op_sel:[0,1,0]
	v_pk_fma_f32 v[178:179], v[6:7], v[116:117], v[178:179] op_sel:[0,1,0]
	v_pk_fma_f32 v[180:181], v[4:5], v[132:133], v[180:181] op_sel:[0,1,0]
	v_pk_fma_f32 v[182:183], v[6:7], v[132:133], v[182:183] op_sel:[0,1,0]
	global_load_dwordx4 v[4:7], v190, s[14:15]
	v_add_u32_e32 v190, 0x6000, v190
	s_waitcnt vmcnt(15)
	v_pk_fma_f32 v[164:165], v[8:9], v[70:71], v[164:165] op_sel_hi:[1,0,1]
	v_pk_fma_f32 v[166:167], v[10:11], v[70:71], v[166:167] op_sel_hi:[1,0,1]
	v_pk_fma_f32 v[168:169], v[8:9], v[86:87], v[168:169] op_sel_hi:[1,0,1]
	v_pk_fma_f32 v[170:171], v[10:11], v[86:87], v[170:171] op_sel_hi:[1,0,1]
	v_pk_fma_f32 v[172:173], v[8:9], v[102:103], v[172:173] op_sel_hi:[1,0,1]
	v_pk_fma_f32 v[174:175], v[10:11], v[102:103], v[174:175] op_sel_hi:[1,0,1]
	v_pk_fma_f32 v[176:177], v[8:9], v[118:119], v[176:177] op_sel_hi:[1,0,1]
	v_pk_fma_f32 v[178:179], v[10:11], v[118:119], v[178:179] op_sel_hi:[1,0,1]
	v_pk_fma_f32 v[180:181], v[8:9], v[134:135], v[180:181] op_sel_hi:[1,0,1]
	v_pk_fma_f32 v[182:183], v[10:11], v[134:135], v[182:183] op_sel_hi:[1,0,1]
	global_load_dwordx4 v[8:11], v190, s[14:15]
	v_add_u32_e32 v190, 0x6000, v190
	s_waitcnt vmcnt(15)
	v_pk_fma_f32 v[164:165], v[12:13], v[70:71], v[164:165] op_sel:[0,1,0]
	v_pk_fma_f32 v[166:167], v[14:15], v[70:71], v[166:167] op_sel:[0,1,0]
	v_pk_fma_f32 v[168:169], v[12:13], v[86:87], v[168:169] op_sel:[0,1,0]
	v_pk_fma_f32 v[170:171], v[14:15], v[86:87], v[170:171] op_sel:[0,1,0]
	v_pk_fma_f32 v[172:173], v[12:13], v[102:103], v[172:173] op_sel:[0,1,0]
	v_pk_fma_f32 v[174:175], v[14:15], v[102:103], v[174:175] op_sel:[0,1,0]
	v_pk_fma_f32 v[176:177], v[12:13], v[118:119], v[176:177] op_sel:[0,1,0]
	v_pk_fma_f32 v[178:179], v[14:15], v[118:119], v[178:179] op_sel:[0,1,0]
	v_pk_fma_f32 v[180:181], v[12:13], v[134:135], v[180:181] op_sel:[0,1,0]
	v_pk_fma_f32 v[182:183], v[14:15], v[134:135], v[182:183] op_sel:[0,1,0]
	global_load_dwordx4 v[12:15], v190, s[14:15]
	v_add_u32_e32 v190, 0x6000, v190
	s_waitcnt vmcnt(15)
	v_pk_fma_f32 v[164:165], v[16:17], v[72:73], v[164:165] op_sel_hi:[1,0,1]
	v_pk_fma_f32 v[166:167], v[18:19], v[72:73], v[166:167] op_sel_hi:[1,0,1]
	v_pk_fma_f32 v[168:169], v[16:17], v[88:89], v[168:169] op_sel_hi:[1,0,1]
	v_pk_fma_f32 v[170:171], v[18:19], v[88:89], v[170:171] op_sel_hi:[1,0,1]
	v_pk_fma_f32 v[172:173], v[16:17], v[104:105], v[172:173] op_sel_hi:[1,0,1]
	v_pk_fma_f32 v[174:175], v[18:19], v[104:105], v[174:175] op_sel_hi:[1,0,1]
	v_pk_fma_f32 v[176:177], v[16:17], v[120:121], v[176:177] op_sel_hi:[1,0,1]
	v_pk_fma_f32 v[178:179], v[18:19], v[120:121], v[178:179] op_sel_hi:[1,0,1]
	v_pk_fma_f32 v[180:181], v[16:17], v[136:137], v[180:181] op_sel_hi:[1,0,1]
	v_pk_fma_f32 v[182:183], v[18:19], v[136:137], v[182:183] op_sel_hi:[1,0,1]
	global_load_dwordx4 v[16:19], v190, s[14:15]
	v_add_u32_e32 v190, 0x6000, v190
	s_waitcnt vmcnt(15)
	v_pk_fma_f32 v[164:165], v[20:21], v[72:73], v[164:165] op_sel:[0,1,0]
	v_pk_fma_f32 v[166:167], v[22:23], v[72:73], v[166:167] op_sel:[0,1,0]
	v_pk_fma_f32 v[168:169], v[20:21], v[88:89], v[168:169] op_sel:[0,1,0]
	v_pk_fma_f32 v[170:171], v[22:23], v[88:89], v[170:171] op_sel:[0,1,0]
	v_pk_fma_f32 v[172:173], v[20:21], v[104:105], v[172:173] op_sel:[0,1,0]
	v_pk_fma_f32 v[174:175], v[22:23], v[104:105], v[174:175] op_sel:[0,1,0]
	v_pk_fma_f32 v[176:177], v[20:21], v[120:121], v[176:177] op_sel:[0,1,0]
	v_pk_fma_f32 v[178:179], v[22:23], v[120:121], v[178:179] op_sel:[0,1,0]
	v_pk_fma_f32 v[180:181], v[20:21], v[136:137], v[180:181] op_sel:[0,1,0]
	v_pk_fma_f32 v[182:183], v[22:23], v[136:137], v[182:183] op_sel:[0,1,0]
	global_load_dwordx4 v[20:23], v190, s[14:15]
	v_add_u32_e32 v190, 0x6000, v190
	s_waitcnt vmcnt(15)
	v_pk_fma_f32 v[164:165], v[24:25], v[74:75], v[164:165] op_sel_hi:[1,0,1]
	v_pk_fma_f32 v[166:167], v[26:27], v[74:75], v[166:167] op_sel_hi:[1,0,1]
	v_pk_fma_f32 v[168:169], v[24:25], v[90:91], v[168:169] op_sel_hi:[1,0,1]
	v_pk_fma_f32 v[170:171], v[26:27], v[90:91], v[170:171] op_sel_hi:[1,0,1]
	v_pk_fma_f32 v[172:173], v[24:25], v[106:107], v[172:173] op_sel_hi:[1,0,1]
	v_pk_fma_f32 v[174:175], v[26:27], v[106:107], v[174:175] op_sel_hi:[1,0,1]
	v_pk_fma_f32 v[176:177], v[24:25], v[122:123], v[176:177] op_sel_hi:[1,0,1]
	v_pk_fma_f32 v[178:179], v[26:27], v[122:123], v[178:179] op_sel_hi:[1,0,1]
	v_pk_fma_f32 v[180:181], v[24:25], v[138:139], v[180:181] op_sel_hi:[1,0,1]
	v_pk_fma_f32 v[182:183], v[26:27], v[138:139], v[182:183] op_sel_hi:[1,0,1]
	global_load_dwordx4 v[24:27], v190, s[14:15]
	v_add_u32_e32 v190, 0x6000, v190
	s_waitcnt vmcnt(15)
	v_pk_fma_f32 v[164:165], v[28:29], v[74:75], v[164:165] op_sel:[0,1,0]
	v_pk_fma_f32 v[166:167], v[30:31], v[74:75], v[166:167] op_sel:[0,1,0]
	v_pk_fma_f32 v[168:169], v[28:29], v[90:91], v[168:169] op_sel:[0,1,0]
	v_pk_fma_f32 v[170:171], v[30:31], v[90:91], v[170:171] op_sel:[0,1,0]
	v_pk_fma_f32 v[172:173], v[28:29], v[106:107], v[172:173] op_sel:[0,1,0]
	v_pk_fma_f32 v[174:175], v[30:31], v[106:107], v[174:175] op_sel:[0,1,0]
	v_pk_fma_f32 v[176:177], v[28:29], v[122:123], v[176:177] op_sel:[0,1,0]
	v_pk_fma_f32 v[178:179], v[30:31], v[122:123], v[178:179] op_sel:[0,1,0]
	v_pk_fma_f32 v[180:181], v[28:29], v[138:139], v[180:181] op_sel:[0,1,0]
	v_pk_fma_f32 v[182:183], v[30:31], v[138:139], v[182:183] op_sel:[0,1,0]
	global_load_dwordx4 v[28:31], v190, s[14:15]
	v_add_u32_e32 v190, 0x6000, v190
	s_waitcnt vmcnt(15)
	v_pk_fma_f32 v[164:165], v[32:33], v[76:77], v[164:165] op_sel_hi:[1,0,1]
	v_pk_fma_f32 v[166:167], v[34:35], v[76:77], v[166:167] op_sel_hi:[1,0,1]
	v_pk_fma_f32 v[168:169], v[32:33], v[92:93], v[168:169] op_sel_hi:[1,0,1]
	v_pk_fma_f32 v[170:171], v[34:35], v[92:93], v[170:171] op_sel_hi:[1,0,1]
	v_pk_fma_f32 v[172:173], v[32:33], v[108:109], v[172:173] op_sel_hi:[1,0,1]
	v_pk_fma_f32 v[174:175], v[34:35], v[108:109], v[174:175] op_sel_hi:[1,0,1]
	v_pk_fma_f32 v[176:177], v[32:33], v[124:125], v[176:177] op_sel_hi:[1,0,1]
	v_pk_fma_f32 v[178:179], v[34:35], v[124:125], v[178:179] op_sel_hi:[1,0,1]
	v_pk_fma_f32 v[180:181], v[32:33], v[140:141], v[180:181] op_sel_hi:[1,0,1]
	v_pk_fma_f32 v[182:183], v[34:35], v[140:141], v[182:183] op_sel_hi:[1,0,1]
	global_load_dwordx4 v[32:35], v190, s[14:15]
	v_add_u32_e32 v190, 0x6000, v190
	s_waitcnt vmcnt(15)
	v_pk_fma_f32 v[164:165], v[36:37], v[76:77], v[164:165] op_sel:[0,1,0]
	v_pk_fma_f32 v[166:167], v[38:39], v[76:77], v[166:167] op_sel:[0,1,0]
	v_pk_fma_f32 v[168:169], v[36:37], v[92:93], v[168:169] op_sel:[0,1,0]
	v_pk_fma_f32 v[170:171], v[38:39], v[92:93], v[170:171] op_sel:[0,1,0]
	v_pk_fma_f32 v[172:173], v[36:37], v[108:109], v[172:173] op_sel:[0,1,0]
	v_pk_fma_f32 v[174:175], v[38:39], v[108:109], v[174:175] op_sel:[0,1,0]
	v_pk_fma_f32 v[176:177], v[36:37], v[124:125], v[176:177] op_sel:[0,1,0]
	v_pk_fma_f32 v[178:179], v[38:39], v[124:125], v[178:179] op_sel:[0,1,0]
	v_pk_fma_f32 v[180:181], v[36:37], v[140:141], v[180:181] op_sel:[0,1,0]
	v_pk_fma_f32 v[182:183], v[38:39], v[140:141], v[182:183] op_sel:[0,1,0]
	global_load_dwordx4 v[36:39], v190, s[14:15]
	v_add_u32_e32 v190, 0x6000, v190
	s_waitcnt vmcnt(15)
	v_pk_fma_f32 v[164:165], v[40:41], v[78:79], v[164:165] op_sel_hi:[1,0,1]
	v_pk_fma_f32 v[166:167], v[42:43], v[78:79], v[166:167] op_sel_hi:[1,0,1]
	v_pk_fma_f32 v[168:169], v[40:41], v[94:95], v[168:169] op_sel_hi:[1,0,1]
	v_pk_fma_f32 v[170:171], v[42:43], v[94:95], v[170:171] op_sel_hi:[1,0,1]
	v_pk_fma_f32 v[172:173], v[40:41], v[110:111], v[172:173] op_sel_hi:[1,0,1]
	v_pk_fma_f32 v[174:175], v[42:43], v[110:111], v[174:175] op_sel_hi:[1,0,1]
	v_pk_fma_f32 v[176:177], v[40:41], v[126:127], v[176:177] op_sel_hi:[1,0,1]
	v_pk_fma_f32 v[178:179], v[42:43], v[126:127], v[178:179] op_sel_hi:[1,0,1]
	v_pk_fma_f32 v[180:181], v[40:41], v[142:143], v[180:181] op_sel_hi:[1,0,1]
	v_pk_fma_f32 v[182:183], v[42:43], v[142:143], v[182:183] op_sel_hi:[1,0,1]
	global_load_dwordx4 v[40:43], v190, s[14:15]
	v_add_u32_e32 v190, 0x6000, v190
	s_waitcnt vmcnt(15)
	v_pk_fma_f32 v[164:165], v[48:49], v[78:79], v[164:165] op_sel:[0,1,0]
	v_pk_fma_f32 v[166:167], v[50:51], v[78:79], v[166:167] op_sel:[0,1,0]
	v_pk_fma_f32 v[168:169], v[48:49], v[94:95], v[168:169] op_sel:[0,1,0]
	v_pk_fma_f32 v[170:171], v[50:51], v[94:95], v[170:171] op_sel:[0,1,0]
	v_pk_fma_f32 v[172:173], v[48:49], v[110:111], v[172:173] op_sel:[0,1,0]
	v_pk_fma_f32 v[174:175], v[50:51], v[110:111], v[174:175] op_sel:[0,1,0]
	v_pk_fma_f32 v[176:177], v[48:49], v[126:127], v[176:177] op_sel:[0,1,0]
	v_pk_fma_f32 v[178:179], v[50:51], v[126:127], v[178:179] op_sel:[0,1,0]
	v_pk_fma_f32 v[180:181], v[48:49], v[142:143], v[180:181] op_sel:[0,1,0]
	v_pk_fma_f32 v[182:183], v[50:51], v[142:143], v[182:183] op_sel:[0,1,0]
	global_load_dwordx4 v[48:51], v190, s[14:15]
	v_add_u32_e32 v190, 0x6000, v190
	s_waitcnt vmcnt(15)
	v_pk_fma_f32 v[164:165], v[52:53], v[80:81], v[164:165] op_sel_hi:[1,0,1]
	v_pk_fma_f32 v[166:167], v[54:55], v[80:81], v[166:167] op_sel_hi:[1,0,1]
	v_pk_fma_f32 v[168:169], v[52:53], v[96:97], v[168:169] op_sel_hi:[1,0,1]
	v_pk_fma_f32 v[170:171], v[54:55], v[96:97], v[170:171] op_sel_hi:[1,0,1]
	v_pk_fma_f32 v[172:173], v[52:53], v[112:113], v[172:173] op_sel_hi:[1,0,1]
	v_pk_fma_f32 v[174:175], v[54:55], v[112:113], v[174:175] op_sel_hi:[1,0,1]
	v_pk_fma_f32 v[176:177], v[52:53], v[128:129], v[176:177] op_sel_hi:[1,0,1]
	v_pk_fma_f32 v[178:179], v[54:55], v[128:129], v[178:179] op_sel_hi:[1,0,1]
	v_pk_fma_f32 v[180:181], v[52:53], v[144:145], v[180:181] op_sel_hi:[1,0,1]
	v_pk_fma_f32 v[182:183], v[54:55], v[144:145], v[182:183] op_sel_hi:[1,0,1]
	global_load_dwordx4 v[52:55], v190, s[14:15]
	v_add_u32_e32 v190, 0x6000, v190
	s_waitcnt vmcnt(15)
	v_pk_fma_f32 v[164:165], v[56:57], v[80:81], v[164:165] op_sel:[0,1,0]
	v_pk_fma_f32 v[166:167], v[58:59], v[80:81], v[166:167] op_sel:[0,1,0]
	v_pk_fma_f32 v[168:169], v[56:57], v[96:97], v[168:169] op_sel:[0,1,0]
	v_pk_fma_f32 v[170:171], v[58:59], v[96:97], v[170:171] op_sel:[0,1,0]
	v_pk_fma_f32 v[172:173], v[56:57], v[112:113], v[172:173] op_sel:[0,1,0]
	v_pk_fma_f32 v[174:175], v[58:59], v[112:113], v[174:175] op_sel:[0,1,0]
	v_pk_fma_f32 v[176:177], v[56:57], v[128:129], v[176:177] op_sel:[0,1,0]
	v_pk_fma_f32 v[178:179], v[58:59], v[128:129], v[178:179] op_sel:[0,1,0]
	v_pk_fma_f32 v[180:181], v[56:57], v[144:145], v[180:181] op_sel:[0,1,0]
	v_pk_fma_f32 v[182:183], v[58:59], v[144:145], v[182:183] op_sel:[0,1,0]
	global_load_dwordx4 v[56:59], v190, s[14:15]
	v_add_u32_e32 v190, 0x6000, v190
	s_waitcnt vmcnt(15)
	v_pk_fma_f32 v[164:165], v[60:61], v[82:83], v[164:165] op_sel_hi:[1,0,1]
	v_pk_fma_f32 v[166:167], v[62:63], v[82:83], v[166:167] op_sel_hi:[1,0,1]
	v_pk_fma_f32 v[168:169], v[60:61], v[98:99], v[168:169] op_sel_hi:[1,0,1]
	v_pk_fma_f32 v[170:171], v[62:63], v[98:99], v[170:171] op_sel_hi:[1,0,1]
	v_pk_fma_f32 v[172:173], v[60:61], v[114:115], v[172:173] op_sel_hi:[1,0,1]
	v_pk_fma_f32 v[174:175], v[62:63], v[114:115], v[174:175] op_sel_hi:[1,0,1]
	v_pk_fma_f32 v[176:177], v[60:61], v[130:131], v[176:177] op_sel_hi:[1,0,1]
	v_pk_fma_f32 v[178:179], v[62:63], v[130:131], v[178:179] op_sel_hi:[1,0,1]
	v_pk_fma_f32 v[180:181], v[60:61], v[146:147], v[180:181] op_sel_hi:[1,0,1]
	v_pk_fma_f32 v[182:183], v[62:63], v[146:147], v[182:183] op_sel_hi:[1,0,1]
	global_load_dwordx4 v[60:63], v190, s[14:15]
	v_add_u32_e32 v190, 0x6000, v190
	s_waitcnt vmcnt(15)
	v_pk_fma_f32 v[164:165], v[148:149], v[82:83], v[164:165] op_sel:[0,1,0]
	v_pk_fma_f32 v[166:167], v[150:151], v[82:83], v[166:167] op_sel:[0,1,0]
	v_pk_fma_f32 v[168:169], v[148:149], v[98:99], v[168:169] op_sel:[0,1,0]
	v_pk_fma_f32 v[170:171], v[150:151], v[98:99], v[170:171] op_sel:[0,1,0]
	v_pk_fma_f32 v[172:173], v[148:149], v[114:115], v[172:173] op_sel:[0,1,0]
	v_pk_fma_f32 v[174:175], v[150:151], v[114:115], v[174:175] op_sel:[0,1,0]
	v_pk_fma_f32 v[176:177], v[148:149], v[130:131], v[176:177] op_sel:[0,1,0]
	v_pk_fma_f32 v[178:179], v[150:151], v[130:131], v[178:179] op_sel:[0,1,0]
	v_pk_fma_f32 v[180:181], v[148:149], v[146:147], v[180:181] op_sel:[0,1,0]
	v_pk_fma_f32 v[182:183], v[150:151], v[146:147], v[182:183] op_sel:[0,1,0]
	global_load_dwordx4 v[148:151], v190, s[14:15]
	v_add_u32_e32 v190, 0x6000, v190
	global_load_dwordx4 v[68:71], v161, s[20:21] offset:64
	global_load_dwordx4 v[72:75], v161, s[20:21] offset:80
	global_load_dwordx4 v[76:79], v161, s[20:21] offset:96
	global_load_dwordx4 v[80:83], v161, s[20:21] offset:112
	global_load_dwordx4 v[84:87], v184, s[20:21] offset:64
	global_load_dwordx4 v[88:91], v184, s[20:21] offset:80
	global_load_dwordx4 v[92:95], v184, s[20:21] offset:96
	global_load_dwordx4 v[96:99], v184, s[20:21] offset:112
	global_load_dwordx4 v[100:103], v185, s[20:21] offset:64
	global_load_dwordx4 v[104:107], v185, s[20:21] offset:80
	global_load_dwordx4 v[108:111], v185, s[20:21] offset:96
	global_load_dwordx4 v[112:115], v185, s[20:21] offset:112
	global_load_dwordx4 v[116:119], v186, s[20:21] offset:64
	global_load_dwordx4 v[120:123], v186, s[20:21] offset:80
	global_load_dwordx4 v[124:127], v186, s[20:21] offset:96
	global_load_dwordx4 v[128:131], v186, s[20:21] offset:112
	global_load_dwordx4 v[132:135], v161, s[22:23] offset:64
	global_load_dwordx4 v[136:139], v161, s[22:23] offset:80
	global_load_dwordx4 v[140:143], v161, s[22:23] offset:96
	global_load_dwordx4 v[144:147], v161, s[22:23] offset:112
	s_waitcnt vmcnt(0)
	v_mul_f32_e32 v206, 0xbfb8aa3b, v68
	v_mul_f32_e32 v207, 0xbfb8aa3b, v69
	v_mul_f32_e32 v208, 0xbfb8aa3b, v70
	v_mul_f32_e32 v209, 0xbfb8aa3b, v71
	v_exp_f32_e32 v206, v206
	v_exp_f32_e32 v207, v207
	v_exp_f32_e32 v208, v208
	v_exp_f32_e32 v209, v209
	v_add_f32_e32 v206, 1.0, v206
	v_add_f32_e32 v207, 1.0, v207
	v_add_f32_e32 v208, 1.0, v208
	v_add_f32_e32 v209, 1.0, v209
	v_rcp_f32_e32 v206, v206
	v_rcp_f32_e32 v207, v207
	v_rcp_f32_e32 v208, v208
	v_rcp_f32_e32 v209, v209
	v_mul_f32_e32 v68, v68, v206
	v_mul_f32_e32 v69, v69, v207
	v_mul_f32_e32 v70, v70, v208
	v_mul_f32_e32 v71, v71, v209
	v_mul_f32_e32 v206, 0xbfb8aa3b, v72
	v_mul_f32_e32 v207, 0xbfb8aa3b, v73
	v_mul_f32_e32 v208, 0xbfb8aa3b, v74
	v_mul_f32_e32 v209, 0xbfb8aa3b, v75
	v_exp_f32_e32 v206, v206
	v_exp_f32_e32 v207, v207
	v_exp_f32_e32 v208, v208
	v_exp_f32_e32 v209, v209
	v_add_f32_e32 v206, 1.0, v206
	v_add_f32_e32 v207, 1.0, v207
	v_add_f32_e32 v208, 1.0, v208
	v_add_f32_e32 v209, 1.0, v209
	v_rcp_f32_e32 v206, v206
	v_rcp_f32_e32 v207, v207
	v_rcp_f32_e32 v208, v208
	v_rcp_f32_e32 v209, v209
	v_mul_f32_e32 v72, v72, v206
	v_mul_f32_e32 v73, v73, v207
	v_mul_f32_e32 v74, v74, v208
	v_mul_f32_e32 v75, v75, v209
	v_mul_f32_e32 v206, 0xbfb8aa3b, v76
	v_mul_f32_e32 v207, 0xbfb8aa3b, v77
	v_mul_f32_e32 v208, 0xbfb8aa3b, v78
	v_mul_f32_e32 v209, 0xbfb8aa3b, v79
	v_exp_f32_e32 v206, v206
	v_exp_f32_e32 v207, v207
	v_exp_f32_e32 v208, v208
	v_exp_f32_e32 v209, v209
	v_add_f32_e32 v206, 1.0, v206
	v_add_f32_e32 v207, 1.0, v207
	v_add_f32_e32 v208, 1.0, v208
	v_add_f32_e32 v209, 1.0, v209
	v_rcp_f32_e32 v206, v206
	v_rcp_f32_e32 v207, v207
	v_rcp_f32_e32 v208, v208
	v_rcp_f32_e32 v209, v209
	v_mul_f32_e32 v76, v76, v206
	v_mul_f32_e32 v77, v77, v207
	v_mul_f32_e32 v78, v78, v208
	v_mul_f32_e32 v79, v79, v209
	v_mul_f32_e32 v206, 0xbfb8aa3b, v80
	v_mul_f32_e32 v207, 0xbfb8aa3b, v81
	v_mul_f32_e32 v208, 0xbfb8aa3b, v82
	v_mul_f32_e32 v209, 0xbfb8aa3b, v83
	v_exp_f32_e32 v206, v206
	v_exp_f32_e32 v207, v207
	v_exp_f32_e32 v208, v208
	v_exp_f32_e32 v209, v209
	v_add_f32_e32 v206, 1.0, v206
	v_add_f32_e32 v207, 1.0, v207
	v_add_f32_e32 v208, 1.0, v208
	v_add_f32_e32 v209, 1.0, v209
	v_rcp_f32_e32 v206, v206
	v_rcp_f32_e32 v207, v207
	v_rcp_f32_e32 v208, v208
	v_rcp_f32_e32 v209, v209
	v_mul_f32_e32 v80, v80, v206
	v_mul_f32_e32 v81, v81, v207
	v_mul_f32_e32 v82, v82, v208
	v_mul_f32_e32 v83, v83, v209
	v_mul_f32_e32 v206, 0xbfb8aa3b, v84
	v_mul_f32_e32 v207, 0xbfb8aa3b, v85
	v_mul_f32_e32 v208, 0xbfb8aa3b, v86
	v_mul_f32_e32 v209, 0xbfb8aa3b, v87
	v_exp_f32_e32 v206, v206
	v_exp_f32_e32 v207, v207
	v_exp_f32_e32 v208, v208
	v_exp_f32_e32 v209, v209
	v_add_f32_e32 v206, 1.0, v206
	v_add_f32_e32 v207, 1.0, v207
	v_add_f32_e32 v208, 1.0, v208
	v_add_f32_e32 v209, 1.0, v209
	v_rcp_f32_e32 v206, v206
	v_rcp_f32_e32 v207, v207
	v_rcp_f32_e32 v208, v208
	v_rcp_f32_e32 v209, v209
	v_mul_f32_e32 v84, v84, v206
	v_mul_f32_e32 v85, v85, v207
	v_mul_f32_e32 v86, v86, v208
	v_mul_f32_e32 v87, v87, v209
	v_mul_f32_e32 v206, 0xbfb8aa3b, v88
	v_mul_f32_e32 v207, 0xbfb8aa3b, v89
	v_mul_f32_e32 v208, 0xbfb8aa3b, v90
	v_mul_f32_e32 v209, 0xbfb8aa3b, v91
	v_exp_f32_e32 v206, v206
	v_exp_f32_e32 v207, v207
	v_exp_f32_e32 v208, v208
	v_exp_f32_e32 v209, v209
	v_add_f32_e32 v206, 1.0, v206
	v_add_f32_e32 v207, 1.0, v207
	v_add_f32_e32 v208, 1.0, v208
	v_add_f32_e32 v209, 1.0, v209
	v_rcp_f32_e32 v206, v206
	v_rcp_f32_e32 v207, v207
	v_rcp_f32_e32 v208, v208
	v_rcp_f32_e32 v209, v209
	v_mul_f32_e32 v88, v88, v206
	v_mul_f32_e32 v89, v89, v207
	v_mul_f32_e32 v90, v90, v208
	v_mul_f32_e32 v91, v91, v209
	v_mul_f32_e32 v206, 0xbfb8aa3b, v92
	v_mul_f32_e32 v207, 0xbfb8aa3b, v93
	v_mul_f32_e32 v208, 0xbfb8aa3b, v94
	v_mul_f32_e32 v209, 0xbfb8aa3b, v95
	v_exp_f32_e32 v206, v206
	v_exp_f32_e32 v207, v207
	v_exp_f32_e32 v208, v208
	v_exp_f32_e32 v209, v209
	v_add_f32_e32 v206, 1.0, v206
	v_add_f32_e32 v207, 1.0, v207
	v_add_f32_e32 v208, 1.0, v208
	v_add_f32_e32 v209, 1.0, v209
	v_rcp_f32_e32 v206, v206
	v_rcp_f32_e32 v207, v207
	v_rcp_f32_e32 v208, v208
	v_rcp_f32_e32 v209, v209
	v_mul_f32_e32 v92, v92, v206
	v_mul_f32_e32 v93, v93, v207
	v_mul_f32_e32 v94, v94, v208
	v_mul_f32_e32 v95, v95, v209
	v_mul_f32_e32 v206, 0xbfb8aa3b, v96
	v_mul_f32_e32 v207, 0xbfb8aa3b, v97
	v_mul_f32_e32 v208, 0xbfb8aa3b, v98
	v_mul_f32_e32 v209, 0xbfb8aa3b, v99
	v_exp_f32_e32 v206, v206
	v_exp_f32_e32 v207, v207
	v_exp_f32_e32 v208, v208
	v_exp_f32_e32 v209, v209
	v_add_f32_e32 v206, 1.0, v206
	v_add_f32_e32 v207, 1.0, v207
	v_add_f32_e32 v208, 1.0, v208
	v_add_f32_e32 v209, 1.0, v209
	v_rcp_f32_e32 v206, v206
	v_rcp_f32_e32 v207, v207
	v_rcp_f32_e32 v208, v208
	v_rcp_f32_e32 v209, v209
	v_mul_f32_e32 v96, v96, v206
	v_mul_f32_e32 v97, v97, v207
	v_mul_f32_e32 v98, v98, v208
	v_mul_f32_e32 v99, v99, v209
	v_mul_f32_e32 v206, 0xbfb8aa3b, v100
	v_mul_f32_e32 v207, 0xbfb8aa3b, v101
	v_mul_f32_e32 v208, 0xbfb8aa3b, v102
	v_mul_f32_e32 v209, 0xbfb8aa3b, v103
	v_exp_f32_e32 v206, v206
	v_exp_f32_e32 v207, v207
	v_exp_f32_e32 v208, v208
	v_exp_f32_e32 v209, v209
	v_add_f32_e32 v206, 1.0, v206
	v_add_f32_e32 v207, 1.0, v207
	v_add_f32_e32 v208, 1.0, v208
	v_add_f32_e32 v209, 1.0, v209
	v_rcp_f32_e32 v206, v206
	v_rcp_f32_e32 v207, v207
	v_rcp_f32_e32 v208, v208
	v_rcp_f32_e32 v209, v209
	v_mul_f32_e32 v100, v100, v206
	v_mul_f32_e32 v101, v101, v207
	v_mul_f32_e32 v102, v102, v208
	v_mul_f32_e32 v103, v103, v209
	v_mul_f32_e32 v206, 0xbfb8aa3b, v104
	v_mul_f32_e32 v207, 0xbfb8aa3b, v105
	v_mul_f32_e32 v208, 0xbfb8aa3b, v106
	v_mul_f32_e32 v209, 0xbfb8aa3b, v107
	v_exp_f32_e32 v206, v206
	v_exp_f32_e32 v207, v207
	v_exp_f32_e32 v208, v208
	v_exp_f32_e32 v209, v209
	v_add_f32_e32 v206, 1.0, v206
	v_add_f32_e32 v207, 1.0, v207
	v_add_f32_e32 v208, 1.0, v208
	v_add_f32_e32 v209, 1.0, v209
	v_rcp_f32_e32 v206, v206
	v_rcp_f32_e32 v207, v207
	v_rcp_f32_e32 v208, v208
	v_rcp_f32_e32 v209, v209
	v_mul_f32_e32 v104, v104, v206
	v_mul_f32_e32 v105, v105, v207
	v_mul_f32_e32 v106, v106, v208
	v_mul_f32_e32 v107, v107, v209
	v_mul_f32_e32 v206, 0xbfb8aa3b, v108
	v_mul_f32_e32 v207, 0xbfb8aa3b, v109
	v_mul_f32_e32 v208, 0xbfb8aa3b, v110
	v_mul_f32_e32 v209, 0xbfb8aa3b, v111
	v_exp_f32_e32 v206, v206
	v_exp_f32_e32 v207, v207
	v_exp_f32_e32 v208, v208
	v_exp_f32_e32 v209, v209
	v_add_f32_e32 v206, 1.0, v206
	v_add_f32_e32 v207, 1.0, v207
	v_add_f32_e32 v208, 1.0, v208
	v_add_f32_e32 v209, 1.0, v209
	v_rcp_f32_e32 v206, v206
	v_rcp_f32_e32 v207, v207
	v_rcp_f32_e32 v208, v208
	v_rcp_f32_e32 v209, v209
	v_mul_f32_e32 v108, v108, v206
	v_mul_f32_e32 v109, v109, v207
	v_mul_f32_e32 v110, v110, v208
	v_mul_f32_e32 v111, v111, v209
	v_mul_f32_e32 v206, 0xbfb8aa3b, v112
	v_mul_f32_e32 v207, 0xbfb8aa3b, v113
	v_mul_f32_e32 v208, 0xbfb8aa3b, v114
	v_mul_f32_e32 v209, 0xbfb8aa3b, v115
	v_exp_f32_e32 v206, v206
	v_exp_f32_e32 v207, v207
	v_exp_f32_e32 v208, v208
	v_exp_f32_e32 v209, v209
	v_add_f32_e32 v206, 1.0, v206
	v_add_f32_e32 v207, 1.0, v207
	v_add_f32_e32 v208, 1.0, v208
	v_add_f32_e32 v209, 1.0, v209
	v_rcp_f32_e32 v206, v206
	v_rcp_f32_e32 v207, v207
	v_rcp_f32_e32 v208, v208
	v_rcp_f32_e32 v209, v209
	v_mul_f32_e32 v112, v112, v206
	v_mul_f32_e32 v113, v113, v207
	v_mul_f32_e32 v114, v114, v208
	v_mul_f32_e32 v115, v115, v209
	v_mul_f32_e32 v206, 0xbfb8aa3b, v116
	v_mul_f32_e32 v207, 0xbfb8aa3b, v117
	v_mul_f32_e32 v208, 0xbfb8aa3b, v118
	v_mul_f32_e32 v209, 0xbfb8aa3b, v119
	v_exp_f32_e32 v206, v206
	v_exp_f32_e32 v207, v207
	v_exp_f32_e32 v208, v208
	v_exp_f32_e32 v209, v209
	v_add_f32_e32 v206, 1.0, v206
	v_add_f32_e32 v207, 1.0, v207
	v_add_f32_e32 v208, 1.0, v208
	v_add_f32_e32 v209, 1.0, v209
	v_rcp_f32_e32 v206, v206
	v_rcp_f32_e32 v207, v207
	v_rcp_f32_e32 v208, v208
	v_rcp_f32_e32 v209, v209
	v_mul_f32_e32 v116, v116, v206
	v_mul_f32_e32 v117, v117, v207
	v_mul_f32_e32 v118, v118, v208
	v_mul_f32_e32 v119, v119, v209
	v_mul_f32_e32 v206, 0xbfb8aa3b, v120
	v_mul_f32_e32 v207, 0xbfb8aa3b, v121
	v_mul_f32_e32 v208, 0xbfb8aa3b, v122
	v_mul_f32_e32 v209, 0xbfb8aa3b, v123
	v_exp_f32_e32 v206, v206
	v_exp_f32_e32 v207, v207
	v_exp_f32_e32 v208, v208
	v_exp_f32_e32 v209, v209
	v_add_f32_e32 v206, 1.0, v206
	v_add_f32_e32 v207, 1.0, v207
	v_add_f32_e32 v208, 1.0, v208
	v_add_f32_e32 v209, 1.0, v209
	v_rcp_f32_e32 v206, v206
	v_rcp_f32_e32 v207, v207
	v_rcp_f32_e32 v208, v208
	v_rcp_f32_e32 v209, v209
	v_mul_f32_e32 v120, v120, v206
	v_mul_f32_e32 v121, v121, v207
	v_mul_f32_e32 v122, v122, v208
	v_mul_f32_e32 v123, v123, v209
	v_mul_f32_e32 v206, 0xbfb8aa3b, v124
	v_mul_f32_e32 v207, 0xbfb8aa3b, v125
	v_mul_f32_e32 v208, 0xbfb8aa3b, v126
	v_mul_f32_e32 v209, 0xbfb8aa3b, v127
	v_exp_f32_e32 v206, v206
	v_exp_f32_e32 v207, v207
	v_exp_f32_e32 v208, v208
	v_exp_f32_e32 v209, v209
	v_add_f32_e32 v206, 1.0, v206
	v_add_f32_e32 v207, 1.0, v207
	v_add_f32_e32 v208, 1.0, v208
	v_add_f32_e32 v209, 1.0, v209
	v_rcp_f32_e32 v206, v206
	v_rcp_f32_e32 v207, v207
	v_rcp_f32_e32 v208, v208
	v_rcp_f32_e32 v209, v209
	v_mul_f32_e32 v124, v124, v206
	v_mul_f32_e32 v125, v125, v207
	v_mul_f32_e32 v126, v126, v208
	v_mul_f32_e32 v127, v127, v209
	v_mul_f32_e32 v206, 0xbfb8aa3b, v128
	v_mul_f32_e32 v207, 0xbfb8aa3b, v129
	v_mul_f32_e32 v208, 0xbfb8aa3b, v130
	v_mul_f32_e32 v209, 0xbfb8aa3b, v131
	v_exp_f32_e32 v206, v206
	v_exp_f32_e32 v207, v207
	v_exp_f32_e32 v208, v208
	v_exp_f32_e32 v209, v209
	v_add_f32_e32 v206, 1.0, v206
	v_add_f32_e32 v207, 1.0, v207
	v_add_f32_e32 v208, 1.0, v208
	v_add_f32_e32 v209, 1.0, v209
	v_rcp_f32_e32 v206, v206
	v_rcp_f32_e32 v207, v207
	v_rcp_f32_e32 v208, v208
	v_rcp_f32_e32 v209, v209
	v_mul_f32_e32 v128, v128, v206
	v_mul_f32_e32 v129, v129, v207
	v_mul_f32_e32 v130, v130, v208
	v_mul_f32_e32 v131, v131, v209
	v_mul_f32_e32 v206, 0xbfb8aa3b, v132
	v_mul_f32_e32 v207, 0xbfb8aa3b, v133
	v_mul_f32_e32 v208, 0xbfb8aa3b, v134
	v_mul_f32_e32 v209, 0xbfb8aa3b, v135
	v_exp_f32_e32 v206, v206
	v_exp_f32_e32 v207, v207
	v_exp_f32_e32 v208, v208
	v_exp_f32_e32 v209, v209
	v_add_f32_e32 v206, 1.0, v206
	v_add_f32_e32 v207, 1.0, v207
	v_add_f32_e32 v208, 1.0, v208
	v_add_f32_e32 v209, 1.0, v209
	v_rcp_f32_e32 v206, v206
	v_rcp_f32_e32 v207, v207
	v_rcp_f32_e32 v208, v208
	v_rcp_f32_e32 v209, v209
	v_mul_f32_e32 v132, v132, v206
	v_mul_f32_e32 v133, v133, v207
	v_mul_f32_e32 v134, v134, v208
	v_mul_f32_e32 v135, v135, v209
	v_mul_f32_e32 v206, 0xbfb8aa3b, v136
	v_mul_f32_e32 v207, 0xbfb8aa3b, v137
	v_mul_f32_e32 v208, 0xbfb8aa3b, v138
	v_mul_f32_e32 v209, 0xbfb8aa3b, v139
	v_exp_f32_e32 v206, v206
	v_exp_f32_e32 v207, v207
	v_exp_f32_e32 v208, v208
	v_exp_f32_e32 v209, v209
	v_add_f32_e32 v206, 1.0, v206
	v_add_f32_e32 v207, 1.0, v207
	v_add_f32_e32 v208, 1.0, v208
	v_add_f32_e32 v209, 1.0, v209
	v_rcp_f32_e32 v206, v206
	v_rcp_f32_e32 v207, v207
	v_rcp_f32_e32 v208, v208
	v_rcp_f32_e32 v209, v209
	v_mul_f32_e32 v136, v136, v206
	v_mul_f32_e32 v137, v137, v207
	v_mul_f32_e32 v138, v138, v208
	v_mul_f32_e32 v139, v139, v209
	v_mul_f32_e32 v206, 0xbfb8aa3b, v140
	v_mul_f32_e32 v207, 0xbfb8aa3b, v141
	v_mul_f32_e32 v208, 0xbfb8aa3b, v142
	v_mul_f32_e32 v209, 0xbfb8aa3b, v143
	v_exp_f32_e32 v206, v206
	v_exp_f32_e32 v207, v207
	v_exp_f32_e32 v208, v208
	v_exp_f32_e32 v209, v209
	v_add_f32_e32 v206, 1.0, v206
	v_add_f32_e32 v207, 1.0, v207
	v_add_f32_e32 v208, 1.0, v208
	v_add_f32_e32 v209, 1.0, v209
	v_rcp_f32_e32 v206, v206
	v_rcp_f32_e32 v207, v207
	v_rcp_f32_e32 v208, v208
	v_rcp_f32_e32 v209, v209
	v_mul_f32_e32 v140, v140, v206
	v_mul_f32_e32 v141, v141, v207
	v_mul_f32_e32 v142, v142, v208
	v_mul_f32_e32 v143, v143, v209
	v_mul_f32_e32 v206, 0xbfb8aa3b, v144
	v_mul_f32_e32 v207, 0xbfb8aa3b, v145
	v_mul_f32_e32 v208, 0xbfb8aa3b, v146
	v_mul_f32_e32 v209, 0xbfb8aa3b, v147
	v_exp_f32_e32 v206, v206
	v_exp_f32_e32 v207, v207
	v_exp_f32_e32 v208, v208
	v_exp_f32_e32 v209, v209
	v_add_f32_e32 v206, 1.0, v206
	v_add_f32_e32 v207, 1.0, v207
	v_add_f32_e32 v208, 1.0, v208
	v_add_f32_e32 v209, 1.0, v209
	v_rcp_f32_e32 v206, v206
	v_rcp_f32_e32 v207, v207
	v_rcp_f32_e32 v208, v208
	v_rcp_f32_e32 v209, v209
	v_mul_f32_e32 v144, v144, v206
	v_mul_f32_e32 v145, v145, v207
	v_mul_f32_e32 v146, v146, v208
	v_mul_f32_e32 v147, v147, v209
	s_waitcnt vmcnt(0)
	v_pk_fma_f32 v[164:165], v[0:1], v[68:69], v[164:165] op_sel_hi:[1,0,1]
	v_pk_fma_f32 v[166:167], v[2:3], v[68:69], v[166:167] op_sel_hi:[1,0,1]
	v_pk_fma_f32 v[168:169], v[0:1], v[84:85], v[168:169] op_sel_hi:[1,0,1]
	v_pk_fma_f32 v[170:171], v[2:3], v[84:85], v[170:171] op_sel_hi:[1,0,1]
	v_pk_fma_f32 v[172:173], v[0:1], v[100:101], v[172:173] op_sel_hi:[1,0,1]
	v_pk_fma_f32 v[174:175], v[2:3], v[100:101], v[174:175] op_sel_hi:[1,0,1]
	v_pk_fma_f32 v[176:177], v[0:1], v[116:117], v[176:177] op_sel_hi:[1,0,1]
	v_pk_fma_f32 v[178:179], v[2:3], v[116:117], v[178:179] op_sel_hi:[1,0,1]
	v_pk_fma_f32 v[180:181], v[0:1], v[132:133], v[180:181] op_sel_hi:[1,0,1]
	v_pk_fma_f32 v[182:183], v[2:3], v[132:133], v[182:183] op_sel_hi:[1,0,1]
	s_waitcnt vmcnt(0)
	v_pk_fma_f32 v[164:165], v[4:5], v[68:69], v[164:165] op_sel:[0,1,0]
	v_pk_fma_f32 v[166:167], v[6:7], v[68:69], v[166:167] op_sel:[0,1,0]
	v_pk_fma_f32 v[168:169], v[4:5], v[84:85], v[168:169] op_sel:[0,1,0]
	v_pk_fma_f32 v[170:171], v[6:7], v[84:85], v[170:171] op_sel:[0,1,0]
	v_pk_fma_f32 v[172:173], v[4:5], v[100:101], v[172:173] op_sel:[0,1,0]
	v_pk_fma_f32 v[174:175], v[6:7], v[100:101], v[174:175] op_sel:[0,1,0]
	v_pk_fma_f32 v[176:177], v[4:5], v[116:117], v[176:177] op_sel:[0,1,0]
	v_pk_fma_f32 v[178:179], v[6:7], v[116:117], v[178:179] op_sel:[0,1,0]
	v_pk_fma_f32 v[180:181], v[4:5], v[132:133], v[180:181] op_sel:[0,1,0]
	v_pk_fma_f32 v[182:183], v[6:7], v[132:133], v[182:183] op_sel:[0,1,0]
	s_waitcnt vmcnt(0)
	v_pk_fma_f32 v[164:165], v[8:9], v[70:71], v[164:165] op_sel_hi:[1,0,1]
	v_pk_fma_f32 v[166:167], v[10:11], v[70:71], v[166:167] op_sel_hi:[1,0,1]
	v_pk_fma_f32 v[168:169], v[8:9], v[86:87], v[168:169] op_sel_hi:[1,0,1]
	v_pk_fma_f32 v[170:171], v[10:11], v[86:87], v[170:171] op_sel_hi:[1,0,1]
	v_pk_fma_f32 v[172:173], v[8:9], v[102:103], v[172:173] op_sel_hi:[1,0,1]
	v_pk_fma_f32 v[174:175], v[10:11], v[102:103], v[174:175] op_sel_hi:[1,0,1]
	v_pk_fma_f32 v[176:177], v[8:9], v[118:119], v[176:177] op_sel_hi:[1,0,1]
	v_pk_fma_f32 v[178:179], v[10:11], v[118:119], v[178:179] op_sel_hi:[1,0,1]
	v_pk_fma_f32 v[180:181], v[8:9], v[134:135], v[180:181] op_sel_hi:[1,0,1]
	v_pk_fma_f32 v[182:183], v[10:11], v[134:135], v[182:183] op_sel_hi:[1,0,1]
	s_waitcnt vmcnt(0)
	v_pk_fma_f32 v[164:165], v[12:13], v[70:71], v[164:165] op_sel:[0,1,0]
	v_pk_fma_f32 v[166:167], v[14:15], v[70:71], v[166:167] op_sel:[0,1,0]
	v_pk_fma_f32 v[168:169], v[12:13], v[86:87], v[168:169] op_sel:[0,1,0]
	v_pk_fma_f32 v[170:171], v[14:15], v[86:87], v[170:171] op_sel:[0,1,0]
	v_pk_fma_f32 v[172:173], v[12:13], v[102:103], v[172:173] op_sel:[0,1,0]
	v_pk_fma_f32 v[174:175], v[14:15], v[102:103], v[174:175] op_sel:[0,1,0]
	v_pk_fma_f32 v[176:177], v[12:13], v[118:119], v[176:177] op_sel:[0,1,0]
	v_pk_fma_f32 v[178:179], v[14:15], v[118:119], v[178:179] op_sel:[0,1,0]
	v_pk_fma_f32 v[180:181], v[12:13], v[134:135], v[180:181] op_sel:[0,1,0]
	v_pk_fma_f32 v[182:183], v[14:15], v[134:135], v[182:183] op_sel:[0,1,0]
	s_waitcnt vmcnt(0)
	v_pk_fma_f32 v[164:165], v[16:17], v[72:73], v[164:165] op_sel_hi:[1,0,1]
	v_pk_fma_f32 v[166:167], v[18:19], v[72:73], v[166:167] op_sel_hi:[1,0,1]
	v_pk_fma_f32 v[168:169], v[16:17], v[88:89], v[168:169] op_sel_hi:[1,0,1]
	v_pk_fma_f32 v[170:171], v[18:19], v[88:89], v[170:171] op_sel_hi:[1,0,1]
	v_pk_fma_f32 v[172:173], v[16:17], v[104:105], v[172:173] op_sel_hi:[1,0,1]
	v_pk_fma_f32 v[174:175], v[18:19], v[104:105], v[174:175] op_sel_hi:[1,0,1]
	v_pk_fma_f32 v[176:177], v[16:17], v[120:121], v[176:177] op_sel_hi:[1,0,1]
	v_pk_fma_f32 v[178:179], v[18:19], v[120:121], v[178:179] op_sel_hi:[1,0,1]
	v_pk_fma_f32 v[180:181], v[16:17], v[136:137], v[180:181] op_sel_hi:[1,0,1]
	v_pk_fma_f32 v[182:183], v[18:19], v[136:137], v[182:183] op_sel_hi:[1,0,1]
	s_waitcnt vmcnt(0)
	v_pk_fma_f32 v[164:165], v[20:21], v[72:73], v[164:165] op_sel:[0,1,0]
	v_pk_fma_f32 v[166:167], v[22:23], v[72:73], v[166:167] op_sel:[0,1,0]
	v_pk_fma_f32 v[168:169], v[20:21], v[88:89], v[168:169] op_sel:[0,1,0]
	v_pk_fma_f32 v[170:171], v[22:23], v[88:89], v[170:171] op_sel:[0,1,0]
	v_pk_fma_f32 v[172:173], v[20:21], v[104:105], v[172:173] op_sel:[0,1,0]
	v_pk_fma_f32 v[174:175], v[22:23], v[104:105], v[174:175] op_sel:[0,1,0]
	v_pk_fma_f32 v[176:177], v[20:21], v[120:121], v[176:177] op_sel:[0,1,0]
	v_pk_fma_f32 v[178:179], v[22:23], v[120:121], v[178:179] op_sel:[0,1,0]
	v_pk_fma_f32 v[180:181], v[20:21], v[136:137], v[180:181] op_sel:[0,1,0]
	v_pk_fma_f32 v[182:183], v[22:23], v[136:137], v[182:183] op_sel:[0,1,0]
	s_waitcnt vmcnt(0)
	v_pk_fma_f32 v[164:165], v[24:25], v[74:75], v[164:165] op_sel_hi:[1,0,1]
	v_pk_fma_f32 v[166:167], v[26:27], v[74:75], v[166:167] op_sel_hi:[1,0,1]
	v_pk_fma_f32 v[168:169], v[24:25], v[90:91], v[168:169] op_sel_hi:[1,0,1]
	v_pk_fma_f32 v[170:171], v[26:27], v[90:91], v[170:171] op_sel_hi:[1,0,1]
	v_pk_fma_f32 v[172:173], v[24:25], v[106:107], v[172:173] op_sel_hi:[1,0,1]
	v_pk_fma_f32 v[174:175], v[26:27], v[106:107], v[174:175] op_sel_hi:[1,0,1]
	v_pk_fma_f32 v[176:177], v[24:25], v[122:123], v[176:177] op_sel_hi:[1,0,1]
	v_pk_fma_f32 v[178:179], v[26:27], v[122:123], v[178:179] op_sel_hi:[1,0,1]
	v_pk_fma_f32 v[180:181], v[24:25], v[138:139], v[180:181] op_sel_hi:[1,0,1]
	v_pk_fma_f32 v[182:183], v[26:27], v[138:139], v[182:183] op_sel_hi:[1,0,1]
	s_waitcnt vmcnt(0)
	v_pk_fma_f32 v[164:165], v[28:29], v[74:75], v[164:165] op_sel:[0,1,0]
	v_pk_fma_f32 v[166:167], v[30:31], v[74:75], v[166:167] op_sel:[0,1,0]
	v_pk_fma_f32 v[168:169], v[28:29], v[90:91], v[168:169] op_sel:[0,1,0]
	v_pk_fma_f32 v[170:171], v[30:31], v[90:91], v[170:171] op_sel:[0,1,0]
	v_pk_fma_f32 v[172:173], v[28:29], v[106:107], v[172:173] op_sel:[0,1,0]
	v_pk_fma_f32 v[174:175], v[30:31], v[106:107], v[174:175] op_sel:[0,1,0]
	v_pk_fma_f32 v[176:177], v[28:29], v[122:123], v[176:177] op_sel:[0,1,0]
	v_pk_fma_f32 v[178:179], v[30:31], v[122:123], v[178:179] op_sel:[0,1,0]
	v_pk_fma_f32 v[180:181], v[28:29], v[138:139], v[180:181] op_sel:[0,1,0]
	v_pk_fma_f32 v[182:183], v[30:31], v[138:139], v[182:183] op_sel:[0,1,0]
	s_waitcnt vmcnt(0)
	v_pk_fma_f32 v[164:165], v[32:33], v[76:77], v[164:165] op_sel_hi:[1,0,1]
	v_pk_fma_f32 v[166:167], v[34:35], v[76:77], v[166:167] op_sel_hi:[1,0,1]
	v_pk_fma_f32 v[168:169], v[32:33], v[92:93], v[168:169] op_sel_hi:[1,0,1]
	v_pk_fma_f32 v[170:171], v[34:35], v[92:93], v[170:171] op_sel_hi:[1,0,1]
	v_pk_fma_f32 v[172:173], v[32:33], v[108:109], v[172:173] op_sel_hi:[1,0,1]
	v_pk_fma_f32 v[174:175], v[34:35], v[108:109], v[174:175] op_sel_hi:[1,0,1]
	v_pk_fma_f32 v[176:177], v[32:33], v[124:125], v[176:177] op_sel_hi:[1,0,1]
	v_pk_fma_f32 v[178:179], v[34:35], v[124:125], v[178:179] op_sel_hi:[1,0,1]
	v_pk_fma_f32 v[180:181], v[32:33], v[140:141], v[180:181] op_sel_hi:[1,0,1]
	v_pk_fma_f32 v[182:183], v[34:35], v[140:141], v[182:183] op_sel_hi:[1,0,1]
	s_waitcnt vmcnt(0)
	v_pk_fma_f32 v[164:165], v[36:37], v[76:77], v[164:165] op_sel:[0,1,0]
	v_pk_fma_f32 v[166:167], v[38:39], v[76:77], v[166:167] op_sel:[0,1,0]
	v_pk_fma_f32 v[168:169], v[36:37], v[92:93], v[168:169] op_sel:[0,1,0]
	v_pk_fma_f32 v[170:171], v[38:39], v[92:93], v[170:171] op_sel:[0,1,0]
	v_pk_fma_f32 v[172:173], v[36:37], v[108:109], v[172:173] op_sel:[0,1,0]
	v_pk_fma_f32 v[174:175], v[38:39], v[108:109], v[174:175] op_sel:[0,1,0]
	v_pk_fma_f32 v[176:177], v[36:37], v[124:125], v[176:177] op_sel:[0,1,0]
	v_pk_fma_f32 v[178:179], v[38:39], v[124:125], v[178:179] op_sel:[0,1,0]
	v_pk_fma_f32 v[180:181], v[36:37], v[140:141], v[180:181] op_sel:[0,1,0]
	v_pk_fma_f32 v[182:183], v[38:39], v[140:141], v[182:183] op_sel:[0,1,0]
	s_waitcnt vmcnt(0)
	v_pk_fma_f32 v[164:165], v[40:41], v[78:79], v[164:165] op_sel_hi:[1,0,1]
	v_pk_fma_f32 v[166:167], v[42:43], v[78:79], v[166:167] op_sel_hi:[1,0,1]
	v_pk_fma_f32 v[168:169], v[40:41], v[94:95], v[168:169] op_sel_hi:[1,0,1]
	v_pk_fma_f32 v[170:171], v[42:43], v[94:95], v[170:171] op_sel_hi:[1,0,1]
	v_pk_fma_f32 v[172:173], v[40:41], v[110:111], v[172:173] op_sel_hi:[1,0,1]
	v_pk_fma_f32 v[174:175], v[42:43], v[110:111], v[174:175] op_sel_hi:[1,0,1]
	v_pk_fma_f32 v[176:177], v[40:41], v[126:127], v[176:177] op_sel_hi:[1,0,1]
	v_pk_fma_f32 v[178:179], v[42:43], v[126:127], v[178:179] op_sel_hi:[1,0,1]
	v_pk_fma_f32 v[180:181], v[40:41], v[142:143], v[180:181] op_sel_hi:[1,0,1]
	v_pk_fma_f32 v[182:183], v[42:43], v[142:143], v[182:183] op_sel_hi:[1,0,1]
	s_waitcnt vmcnt(0)
	v_pk_fma_f32 v[164:165], v[48:49], v[78:79], v[164:165] op_sel:[0,1,0]
	v_pk_fma_f32 v[166:167], v[50:51], v[78:79], v[166:167] op_sel:[0,1,0]
	v_pk_fma_f32 v[168:169], v[48:49], v[94:95], v[168:169] op_sel:[0,1,0]
	v_pk_fma_f32 v[170:171], v[50:51], v[94:95], v[170:171] op_sel:[0,1,0]
	v_pk_fma_f32 v[172:173], v[48:49], v[110:111], v[172:173] op_sel:[0,1,0]
	v_pk_fma_f32 v[174:175], v[50:51], v[110:111], v[174:175] op_sel:[0,1,0]
	v_pk_fma_f32 v[176:177], v[48:49], v[126:127], v[176:177] op_sel:[0,1,0]
	v_pk_fma_f32 v[178:179], v[50:51], v[126:127], v[178:179] op_sel:[0,1,0]
	v_pk_fma_f32 v[180:181], v[48:49], v[142:143], v[180:181] op_sel:[0,1,0]
	v_pk_fma_f32 v[182:183], v[50:51], v[142:143], v[182:183] op_sel:[0,1,0]
	s_waitcnt vmcnt(0)
	v_pk_fma_f32 v[164:165], v[52:53], v[80:81], v[164:165] op_sel_hi:[1,0,1]
	v_pk_fma_f32 v[166:167], v[54:55], v[80:81], v[166:167] op_sel_hi:[1,0,1]
	v_pk_fma_f32 v[168:169], v[52:53], v[96:97], v[168:169] op_sel_hi:[1,0,1]
	v_pk_fma_f32 v[170:171], v[54:55], v[96:97], v[170:171] op_sel_hi:[1,0,1]
	v_pk_fma_f32 v[172:173], v[52:53], v[112:113], v[172:173] op_sel_hi:[1,0,1]
	v_pk_fma_f32 v[174:175], v[54:55], v[112:113], v[174:175] op_sel_hi:[1,0,1]
	v_pk_fma_f32 v[176:177], v[52:53], v[128:129], v[176:177] op_sel_hi:[1,0,1]
	v_pk_fma_f32 v[178:179], v[54:55], v[128:129], v[178:179] op_sel_hi:[1,0,1]
	v_pk_fma_f32 v[180:181], v[52:53], v[144:145], v[180:181] op_sel_hi:[1,0,1]
	v_pk_fma_f32 v[182:183], v[54:55], v[144:145], v[182:183] op_sel_hi:[1,0,1]
	s_waitcnt vmcnt(0)
	v_pk_fma_f32 v[164:165], v[56:57], v[80:81], v[164:165] op_sel:[0,1,0]
	v_pk_fma_f32 v[166:167], v[58:59], v[80:81], v[166:167] op_sel:[0,1,0]
	v_pk_fma_f32 v[168:169], v[56:57], v[96:97], v[168:169] op_sel:[0,1,0]
	v_pk_fma_f32 v[170:171], v[58:59], v[96:97], v[170:171] op_sel:[0,1,0]
	v_pk_fma_f32 v[172:173], v[56:57], v[112:113], v[172:173] op_sel:[0,1,0]
	v_pk_fma_f32 v[174:175], v[58:59], v[112:113], v[174:175] op_sel:[0,1,0]
	v_pk_fma_f32 v[176:177], v[56:57], v[128:129], v[176:177] op_sel:[0,1,0]
	v_pk_fma_f32 v[178:179], v[58:59], v[128:129], v[178:179] op_sel:[0,1,0]
	v_pk_fma_f32 v[180:181], v[56:57], v[144:145], v[180:181] op_sel:[0,1,0]
	v_pk_fma_f32 v[182:183], v[58:59], v[144:145], v[182:183] op_sel:[0,1,0]
	s_waitcnt vmcnt(0)
	v_pk_fma_f32 v[164:165], v[60:61], v[82:83], v[164:165] op_sel_hi:[1,0,1]
	v_pk_fma_f32 v[166:167], v[62:63], v[82:83], v[166:167] op_sel_hi:[1,0,1]
	v_pk_fma_f32 v[168:169], v[60:61], v[98:99], v[168:169] op_sel_hi:[1,0,1]
	v_pk_fma_f32 v[170:171], v[62:63], v[98:99], v[170:171] op_sel_hi:[1,0,1]
	v_pk_fma_f32 v[172:173], v[60:61], v[114:115], v[172:173] op_sel_hi:[1,0,1]
	v_pk_fma_f32 v[174:175], v[62:63], v[114:115], v[174:175] op_sel_hi:[1,0,1]
	v_pk_fma_f32 v[176:177], v[60:61], v[130:131], v[176:177] op_sel_hi:[1,0,1]
	v_pk_fma_f32 v[178:179], v[62:63], v[130:131], v[178:179] op_sel_hi:[1,0,1]
	v_pk_fma_f32 v[180:181], v[60:61], v[146:147], v[180:181] op_sel_hi:[1,0,1]
	v_pk_fma_f32 v[182:183], v[62:63], v[146:147], v[182:183] op_sel_hi:[1,0,1]
	s_waitcnt vmcnt(0)
	v_pk_fma_f32 v[164:165], v[148:149], v[82:83], v[164:165] op_sel:[0,1,0]
	v_pk_fma_f32 v[166:167], v[150:151], v[82:83], v[166:167] op_sel:[0,1,0]
	v_pk_fma_f32 v[168:169], v[148:149], v[98:99], v[168:169] op_sel:[0,1,0]
	v_pk_fma_f32 v[170:171], v[150:151], v[98:99], v[170:171] op_sel:[0,1,0]
	v_pk_fma_f32 v[172:173], v[148:149], v[114:115], v[172:173] op_sel:[0,1,0]
	v_pk_fma_f32 v[174:175], v[150:151], v[114:115], v[174:175] op_sel:[0,1,0]
	v_pk_fma_f32 v[176:177], v[148:149], v[130:131], v[176:177] op_sel:[0,1,0]
	v_pk_fma_f32 v[178:179], v[150:151], v[130:131], v[178:179] op_sel:[0,1,0]
	v_pk_fma_f32 v[180:181], v[148:149], v[146:147], v[180:181] op_sel:[0,1,0]
	v_pk_fma_f32 v[182:183], v[150:151], v[146:147], v[182:183] op_sel:[0,1,0]
	global_store_dwordx4 v191, v[164:167], s[24:25]
	s_add_u32 s24, s24, 0x6000
	s_addc_u32 s25, s25, 0
	global_store_dwordx4 v191, v[168:171], s[24:25]
	s_add_u32 s24, s24, 0x6000
	s_addc_u32 s25, s25, 0
	global_store_dwordx4 v191, v[172:175], s[24:25]
	s_add_u32 s24, s24, 0x6000
	s_addc_u32 s25, s25, 0
	global_store_dwordx4 v191, v[176:179], s[24:25]
	s_add_u32 s24, s24, 0x6000
	s_addc_u32 s25, s25, 0
	global_store_dwordx4 v191, v[180:183], s[24:25]
	s_add_u32 s12, s12, s13
	s_cmp_lt_u32 s12, 0x600
	s_cbranch_scc1 .Lmods_item
